# v8 + transposes rebalanced: workgroups with one SGU unit take 3 transpose tiles, those with two take none (balances the merged p2a+p2b phase)
# speedup vs baseline: 1.0118x; 1.0118x over previous
.LBB0_725:
	s_sub_i32 s0, s24, 0x80
	s_mov_b32 s82, 0x60000
	s_cmp_lt_i32 s0, 0
	s_nop 0
	s_cbranch_scc1 .LBB0_728
	v_ashrrev_i32_e32 v38, 3, v193
	v_lshl_add_u32 v2, s58, 6, v38
	v_and_b32_e32 v3, 56, v153
	v_lshlrev_b32_e32 v0, 1, v3
	s_waitcnt vmcnt(3)
	v_add_u32_e32 v6, 8, v2
	s_waitcnt vmcnt(0)
	v_lshl_add_u64 v[18:19], s[16:17], 0, v[0:1]
	v_mad_i64_i32 v[22:23], s[16:17], v6, s8, 0
	v_add_u32_e32 v6, 16, v2
	v_mad_i64_i32 v[24:25], s[16:17], v6, s8, 0
	v_add_u32_e32 v6, 24, v2
	v_mad_i64_i32 v[26:27], s[16:17], v6, s8, 0
	v_add_u32_e32 v6, 32, v2
	s_mul_i32 s1, s25, 0x2100
	v_lshlrev_b32_e32 v4, 4, v193
	v_mad_i64_i32 v[28:29], s[16:17], v6, s8, 0
	v_add_u32_e32 v6, 40, v2
	s_add_i32 s1, s1, 0
	v_and_b32_e32 v4, 0x70, v4
	v_add_u32_e32 v39, 56, v38
	v_mad_i64_i32 v[30:31], s[16:17], v6, s8, 0
	v_add_u32_e32 v6, 48, v2
	v_add_u32_e32 v40, 8, v38
	v_add_u32_e32 v41, 16, v38
	v_add_u32_e32 v42, 24, v38
	v_add_u32_e32 v43, 32, v38
	v_add_u32_e32 v44, 40, v38
	v_add_u32_e32 v45, 48, v38
	v_add_u32_e32 v4, s1, v4
	v_lshl_add_u32 v5, v39, 1, s1
	s_lshl_b32 s10, s25, 4
	v_mad_i64_i32 v[32:33], s[16:17], v6, s8, 0
	v_lshl_add_u32 v6, v38, 1, s1
	v_lshl_add_u32 v7, v40, 1, s1
	v_lshl_add_u32 v8, v41, 1, s1
	v_lshl_add_u32 v9, v42, 1, s1
	v_lshl_add_u32 v10, v43, 1, s1
	v_lshl_add_u32 v11, v44, 1, s1
	v_lshl_add_u32 v12, v45, 1, s1
	s_lshl_b32 s1, s58, 7
	v_mad_i64_i32 v[20:21], s[16:17], v2, s8, 0
	v_add_u32_e32 v2, 56, v2
	s_add_u32 s14, s14, s1
	v_mad_i64_i32 v[34:35], s[16:17], v2, s8, 0
	s_addc_u32 s15, s15, 0
	s_movk_i32 s1, 0x4000
	s_movk_i32 s16, 0x84
	v_lshl_add_u64 v[36:37], s[14:15], 0, v[0:1]
	s_sub_i32 s10, s10, s1
	s_lshl_b32 s14, s24, 7
	v_mul_u32_u24_e32 v3, 0x84, v3
	v_mul_lo_u32 v2, v38, s16
	s_add_i32 s10, s10, s14
	s_nop 0
	v_add_u32_e32 v0, v4, v2
	v_add_u32_e32 v46, v6, v3
	v_add_u32_e32 v47, v7, v3
	v_add_u32_e32 v48, v8, v3
	v_add_u32_e32 v49, v9, v3
	v_add_u32_e32 v50, v10, v3
	v_add_u32_e32 v51, v11, v3
	v_add_u32_e32 v52, v12, v3
	v_add_u32_e32 v53, v5, v3
.LBB0_727:
	s_and_b32 s14, s10, 0xffffffc0
	s_ashr_i32 s15, s14, 31
	v_lshl_add_u64 v[2:3], s[14:15], 1, v[18:19]
	v_lshl_add_u64 v[4:5], v[2:3], 0, v[20:21]
	v_lshl_add_u64 v[6:7], v[2:3], 0, v[22:23]
	global_load_dwordx4 v[54:57], v[4:5], off
	global_load_dwordx4 v[58:61], v[6:7], off
	v_lshl_add_u64 v[4:5], v[2:3], 0, v[24:25]
	v_lshl_add_u64 v[6:7], v[2:3], 0, v[26:27]
	global_load_dwordx4 v[62:65], v[4:5], off
	global_load_dwordx4 v[66:69], v[6:7], off
	v_lshl_add_u64 v[4:5], v[2:3], 0, v[28:29]
	v_lshl_add_u64 v[6:7], v[2:3], 0, v[30:31]
	global_load_dwordx4 v[70:73], v[4:5], off
	global_load_dwordx4 v[74:77], v[6:7], off
	v_lshl_add_u64 v[4:5], v[2:3], 0, v[32:33]
	v_lshl_add_u64 v[2:3], v[2:3], 0, v[34:35]
	v_add_u32_e32 v6, s14, v38
	global_load_dwordx4 v[78:81], v[4:5], off
	global_load_dwordx4 v[82:85], v[2:3], off
	v_add_u32_e32 v2, 8, v6
	v_mad_i64_i32 v[102:103], s[16:17], v6, s9, v[36:37]
	v_mad_i64_i32 v[2:3], s[16:17], v2, s9, v[36:37]
	global_load_dwordx4 v[86:89], v[102:103], off offset:1024
	global_load_dwordx4 v[90:93], v[2:3], off offset:1024
	v_add_u32_e32 v2, 16, v6
	v_add_u32_e32 v4, 24, v6
	v_mad_i64_i32 v[2:3], s[16:17], v2, s9, v[36:37]
	v_mad_i64_i32 v[4:5], s[16:17], v4, s9, v[36:37]
	global_load_dwordx4 v[94:97], v[2:3], off offset:1024
	global_load_dwordx4 v[98:101], v[4:5], off offset:1024
	v_add_u32_e32 v2, 32, v6
	v_add_u32_e32 v4, 40, v6
	v_mad_i64_i32 v[2:3], s[16:17], v2, s9, v[36:37]
	v_mad_i64_i32 v[4:5], s[16:17], v4, s9, v[36:37]
	global_load_dwordx4 v[14:17], v[2:3], off offset:1024
	global_load_dwordx4 v[10:13], v[4:5], off offset:1024
	v_add_u32_e32 v2, 48, v6
	v_add_u32_e32 v4, 56, v6
	v_mad_i64_i32 v[2:3], s[16:17], v2, s9, v[36:37]
	v_mad_i64_i32 v[4:5], s[16:17], v4, s9, v[36:37]
	global_load_dwordx4 v[6:9], v[2:3], off offset:1024
	s_nop 0
	global_load_dwordx4 v[2:5], v[4:5], off offset:1024
	s_waitcnt vmcnt(15)
	ds_write2_b32 v0, v54, v55 offset1:1
	ds_write2_b32 v0, v56, v57 offset0:2 offset1:3
	v_add_u32_e32 v54, 0x420, v0
	s_waitcnt vmcnt(14)
	ds_write2_b32 v54, v58, v59 offset1:1
	v_add_u32_e32 v54, 0x428, v0
	ds_write2_b32 v54, v60, v61 offset1:1
	v_add_u32_e32 v54, 0x840, v0
	s_waitcnt vmcnt(13)
	ds_write2_b32 v54, v62, v63 offset1:1
	v_add_u32_e32 v54, 0x848, v0
	ds_write2_b32 v54, v64, v65 offset1:1
	v_add_u32_e32 v54, 0xc60, v0
	s_waitcnt vmcnt(12)
	ds_write2_b32 v54, v66, v67 offset1:1
	v_add_u32_e32 v54, 0xc68, v0
	ds_write2_b32 v54, v68, v69 offset1:1
	v_add_u32_e32 v54, 0x1080, v0
	s_waitcnt vmcnt(11)
	ds_write2_b32 v54, v70, v71 offset1:1
	v_add_u32_e32 v54, 0x1088, v0
	ds_write2_b32 v54, v72, v73 offset1:1
	v_add_u32_e32 v54, 0x14a0, v0
	s_waitcnt vmcnt(10)
	ds_write2_b32 v54, v74, v75 offset1:1
	v_add_u32_e32 v54, 0x14a8, v0
	ds_write2_b32 v54, v76, v77 offset1:1
	v_add_u32_e32 v54, 0x18c0, v0
	s_waitcnt vmcnt(9)
	ds_write2_b32 v54, v78, v79 offset1:1
	v_add_u32_e32 v54, 0x18c8, v0
	ds_write2_b32 v54, v80, v81 offset1:1
	v_add_u32_e32 v54, 0x1ce0, v0
	s_waitcnt vmcnt(8)
	ds_write2_b32 v54, v82, v83 offset1:1
	v_add_u32_e32 v54, 0x1ce8, v0
	ds_write2_b32 v54, v84, v85 offset1:1
	s_waitcnt lgkmcnt(0)
	ds_read_u16 v62, v46
	ds_read_u16 v63, v46 offset:132
	ds_read_u16 v64, v46 offset:264
	ds_read_u16 v65, v46 offset:396
	ds_read_u16 v66, v46 offset:528
	ds_read_u16 v67, v46 offset:660
	ds_read_u16 v68, v46 offset:792
	ds_read_u16 v69, v46 offset:924
	s_waitcnt lgkmcnt(7)
	v_cvt_f32_f16_e32 v62, v62
	s_waitcnt lgkmcnt(6)
	v_cvt_f32_f16_e32 v63, v63
	s_waitcnt lgkmcnt(5)
	v_cvt_f32_f16_e32 v64, v64
	s_waitcnt lgkmcnt(4)
	v_cvt_f32_f16_e32 v65, v65
	s_waitcnt vmcnt(7)
	v_lshlrev_b32_e32 v54, 16, v86
	v_and_b32_e32 v55, 0xffff0000, v86
	v_lshlrev_b32_e32 v56, 16, v87
	v_and_b32_e32 v57, 0xffff0000, v87
	v_mul_f32_e32 v54, v54, v62
	v_mul_f32_e32 v55, v55, v63
	v_mul_f32_e32 v56, v56, v64
	v_mul_f32_e32 v57, v57, v65
	s_waitcnt lgkmcnt(3)
	v_cvt_f32_f16_e32 v62, v66
	s_waitcnt lgkmcnt(2)
	v_cvt_f32_f16_e32 v63, v67
	s_waitcnt lgkmcnt(1)
	v_cvt_f32_f16_e32 v64, v68
	s_waitcnt lgkmcnt(0)
	v_cvt_f32_f16_e32 v65, v69
	v_lshlrev_b32_e32 v58, 16, v88
	v_and_b32_e32 v59, 0xffff0000, v88
	v_lshlrev_b32_e32 v60, 16, v89
	v_and_b32_e32 v61, 0xffff0000, v89
	v_mul_f32_e32 v58, v58, v62
	v_mul_f32_e32 v59, v59, v63
	v_mul_f32_e32 v60, v60, v64
	v_mul_f32_e32 v61, v61, v65
	v_cvt_pk_bf16_f32 v54, v54, v55
	v_cvt_pk_bf16_f32 v55, v56, v57
	v_cvt_pk_bf16_f32 v56, v58, v59
	v_cvt_pk_bf16_f32 v57, v60, v61
	global_store_dwordx4 v[102:103], v[54:57], off offset:1024
	ds_read_u16 v63, v47
	ds_read_u16 v64, v47 offset:132
	ds_read_u16 v65, v47 offset:264
	ds_read_u16 v66, v47 offset:396
	ds_read_u16 v67, v47 offset:528
	ds_read_u16 v68, v47 offset:660
	ds_read_u16 v69, v47 offset:792
	ds_read_u16 v70, v47 offset:924
	s_waitcnt lgkmcnt(7)
	v_cvt_f32_f16_e32 v63, v63
	s_waitcnt lgkmcnt(6)
	v_cvt_f32_f16_e32 v64, v64
	s_waitcnt lgkmcnt(5)
	v_cvt_f32_f16_e32 v65, v65
	s_waitcnt lgkmcnt(4)
	v_cvt_f32_f16_e32 v66, v66
	s_waitcnt vmcnt(7)
	v_lshlrev_b32_e32 v55, 16, v90
	v_and_b32_e32 v56, 0xffff0000, v90
	v_lshlrev_b32_e32 v57, 16, v91
	v_and_b32_e32 v58, 0xffff0000, v91
	v_mul_f32_e32 v55, v55, v63
	v_mul_f32_e32 v56, v56, v64
	v_mul_f32_e32 v57, v57, v65
	v_mul_f32_e32 v63, v58, v66
	s_waitcnt lgkmcnt(3)
	v_cvt_f32_f16_e32 v58, v67
	s_waitcnt lgkmcnt(2)
	v_cvt_f32_f16_e32 v64, v68
	s_waitcnt lgkmcnt(1)
	v_cvt_f32_f16_e32 v65, v69
	s_waitcnt lgkmcnt(0)
	v_cvt_f32_f16_e32 v66, v70
	v_lshlrev_b32_e32 v59, 16, v92
	v_and_b32_e32 v60, 0xffff0000, v92
	v_lshlrev_b32_e32 v61, 16, v93
	v_and_b32_e32 v62, 0xffff0000, v93
	v_add_u32_e32 v54, s14, v40
	v_mul_f32_e32 v67, v59, v58
	v_mul_f32_e32 v60, v60, v64
	v_mul_f32_e32 v61, v61, v65
	v_mul_f32_e32 v62, v62, v66
	v_mad_i64_i32 v[58:59], s[16:17], v54, s9, v[36:37]
	v_cvt_pk_bf16_f32 v54, v55, v56
	v_cvt_pk_bf16_f32 v55, v57, v63
	v_cvt_pk_bf16_f32 v56, v67, v60
	v_cvt_pk_bf16_f32 v57, v61, v62
	global_store_dwordx4 v[58:59], v[54:57], off offset:1024
	ds_read_u16 v63, v48
	ds_read_u16 v64, v48 offset:132
	ds_read_u16 v65, v48 offset:264
	ds_read_u16 v66, v48 offset:396
	ds_read_u16 v67, v48 offset:528
	ds_read_u16 v68, v48 offset:660
	ds_read_u16 v69, v48 offset:792
	ds_read_u16 v70, v48 offset:924
	s_waitcnt lgkmcnt(7)
	v_cvt_f32_f16_e32 v63, v63
	s_waitcnt lgkmcnt(6)
	v_cvt_f32_f16_e32 v64, v64
	s_waitcnt lgkmcnt(5)
	v_cvt_f32_f16_e32 v65, v65
	s_waitcnt lgkmcnt(4)
	v_cvt_f32_f16_e32 v66, v66
	s_waitcnt vmcnt(7)
	v_lshlrev_b32_e32 v55, 16, v94
	v_and_b32_e32 v56, 0xffff0000, v94
	v_lshlrev_b32_e32 v57, 16, v95
	v_and_b32_e32 v58, 0xffff0000, v95
	v_mul_f32_e32 v55, v55, v63
	v_mul_f32_e32 v56, v56, v64
	v_mul_f32_e32 v57, v57, v65
	v_mul_f32_e32 v63, v58, v66
	s_waitcnt lgkmcnt(3)
	v_cvt_f32_f16_e32 v58, v67
	s_waitcnt lgkmcnt(2)
	v_cvt_f32_f16_e32 v64, v68
	s_waitcnt lgkmcnt(1)
	v_cvt_f32_f16_e32 v65, v69
	s_waitcnt lgkmcnt(0)
	v_cvt_f32_f16_e32 v66, v70
	v_lshlrev_b32_e32 v59, 16, v96
	v_and_b32_e32 v60, 0xffff0000, v96
	v_lshlrev_b32_e32 v61, 16, v97
	v_and_b32_e32 v62, 0xffff0000, v97
	v_add_u32_e32 v54, s14, v41
	v_mul_f32_e32 v67, v59, v58
	v_mul_f32_e32 v60, v60, v64
	v_mul_f32_e32 v61, v61, v65
	v_mul_f32_e32 v62, v62, v66
	v_mad_i64_i32 v[58:59], s[16:17], v54, s9, v[36:37]
	v_cvt_pk_bf16_f32 v54, v55, v56
	v_cvt_pk_bf16_f32 v55, v57, v63
	v_cvt_pk_bf16_f32 v56, v67, v60
	v_cvt_pk_bf16_f32 v57, v61, v62
	global_store_dwordx4 v[58:59], v[54:57], off offset:1024
	ds_read_u16 v63, v49
	ds_read_u16 v64, v49 offset:132
	ds_read_u16 v65, v49 offset:264
	ds_read_u16 v66, v49 offset:396
	ds_read_u16 v67, v49 offset:528
	ds_read_u16 v68, v49 offset:660
	ds_read_u16 v69, v49 offset:792
	ds_read_u16 v70, v49 offset:924
	s_waitcnt lgkmcnt(7)
	v_cvt_f32_f16_e32 v63, v63
	s_waitcnt lgkmcnt(6)
	v_cvt_f32_f16_e32 v64, v64
	s_waitcnt lgkmcnt(5)
	v_cvt_f32_f16_e32 v65, v65
	s_waitcnt lgkmcnt(4)
	v_cvt_f32_f16_e32 v66, v66
	s_waitcnt vmcnt(7)
	v_lshlrev_b32_e32 v55, 16, v98
	v_and_b32_e32 v56, 0xffff0000, v98
	v_lshlrev_b32_e32 v57, 16, v99
	v_and_b32_e32 v58, 0xffff0000, v99
	v_mul_f32_e32 v55, v55, v63
	v_mul_f32_e32 v56, v56, v64
	v_mul_f32_e32 v57, v57, v65
	v_mul_f32_e32 v63, v58, v66
	s_waitcnt lgkmcnt(3)
	v_cvt_f32_f16_e32 v58, v67
	s_waitcnt lgkmcnt(2)
	v_cvt_f32_f16_e32 v64, v68
	s_waitcnt lgkmcnt(1)
	v_cvt_f32_f16_e32 v65, v69
	s_waitcnt lgkmcnt(0)
	v_cvt_f32_f16_e32 v66, v70
	v_lshlrev_b32_e32 v59, 16, v100
	v_and_b32_e32 v60, 0xffff0000, v100
	v_lshlrev_b32_e32 v61, 16, v101
	v_and_b32_e32 v62, 0xffff0000, v101
	v_add_u32_e32 v54, s14, v42
	v_mul_f32_e32 v67, v59, v58
	v_mul_f32_e32 v60, v60, v64
	v_mul_f32_e32 v61, v61, v65
	v_mul_f32_e32 v62, v62, v66
	v_mad_i64_i32 v[58:59], s[16:17], v54, s9, v[36:37]
	v_cvt_pk_bf16_f32 v54, v55, v56
	v_cvt_pk_bf16_f32 v55, v57, v63
	v_cvt_pk_bf16_f32 v56, v67, v60
	v_cvt_pk_bf16_f32 v57, v61, v62
	global_store_dwordx4 v[58:59], v[54:57], off offset:1024
	ds_read_u16 v59, v50
	ds_read_u16 v60, v50 offset:132
	ds_read_u16 v61, v50 offset:264
	ds_read_u16 v62, v50 offset:396
	ds_read_u16 v63, v50 offset:528
	ds_read_u16 v64, v50 offset:660
	ds_read_u16 v65, v50 offset:792
	ds_read_u16 v66, v50 offset:924
	s_waitcnt lgkmcnt(7)
	v_cvt_f32_f16_e32 v59, v59
	s_waitcnt lgkmcnt(6)
	v_cvt_f32_f16_e32 v60, v60
	s_waitcnt lgkmcnt(5)
	v_cvt_f32_f16_e32 v61, v61
	s_waitcnt lgkmcnt(4)
	v_cvt_f32_f16_e32 v62, v62
	s_waitcnt vmcnt(7)
	v_lshlrev_b32_e32 v55, 16, v14
	v_and_b32_e32 v14, 0xffff0000, v14
	v_lshlrev_b32_e32 v56, 16, v15
	v_and_b32_e32 v15, 0xffff0000, v15
	v_mul_f32_e32 v59, v55, v59
	v_mul_f32_e32 v14, v14, v60
	v_mul_f32_e32 v56, v56, v61
	v_mul_f32_e32 v15, v15, v62
	s_waitcnt lgkmcnt(3)
	v_cvt_f32_f16_e32 v55, v63
	s_waitcnt lgkmcnt(2)
	v_cvt_f32_f16_e32 v60, v64
	s_waitcnt lgkmcnt(1)
	v_cvt_f32_f16_e32 v61, v65
	s_waitcnt lgkmcnt(0)
	v_cvt_f32_f16_e32 v62, v66
	v_lshlrev_b32_e32 v57, 16, v16
	v_and_b32_e32 v16, 0xffff0000, v16
	v_lshlrev_b32_e32 v58, 16, v17
	v_and_b32_e32 v17, 0xffff0000, v17
	v_add_u32_e32 v54, s14, v43
	v_mul_f32_e32 v57, v57, v55
	v_mul_f32_e32 v16, v16, v60
	v_mul_f32_e32 v58, v58, v61
	v_mul_f32_e32 v17, v17, v62
	v_mad_i64_i32 v[54:55], s[16:17], v54, s9, v[36:37]
	v_cvt_pk_bf16_f32 v14, v59, v14
	v_cvt_pk_bf16_f32 v15, v56, v15
	v_cvt_pk_bf16_f32 v16, v57, v16
	v_cvt_pk_bf16_f32 v17, v58, v17
	global_store_dwordx4 v[54:55], v[14:17], off offset:1024
	ds_read_u16 v55, v51
	ds_read_u16 v56, v51 offset:132
	ds_read_u16 v57, v51 offset:264
	ds_read_u16 v58, v51 offset:396
	ds_read_u16 v59, v51 offset:528
	ds_read_u16 v60, v51 offset:660
	ds_read_u16 v61, v51 offset:792
	ds_read_u16 v62, v51 offset:924
	s_waitcnt lgkmcnt(7)
	v_cvt_f32_f16_e32 v55, v55
	s_waitcnt lgkmcnt(6)
	v_cvt_f32_f16_e32 v56, v56
	s_waitcnt lgkmcnt(5)
	v_cvt_f32_f16_e32 v57, v57
	s_waitcnt lgkmcnt(4)
	v_cvt_f32_f16_e32 v58, v58
	s_waitcnt vmcnt(7)
	v_lshlrev_b32_e32 v15, 16, v10
	v_and_b32_e32 v10, 0xffff0000, v10
	v_lshlrev_b32_e32 v16, 16, v11
	v_and_b32_e32 v11, 0xffff0000, v11
	v_mul_f32_e32 v55, v15, v55
	v_mul_f32_e32 v10, v10, v56
	v_mul_f32_e32 v16, v16, v57
	v_mul_f32_e32 v11, v11, v58
	s_waitcnt lgkmcnt(3)
	v_cvt_f32_f16_e32 v15, v59
	s_waitcnt lgkmcnt(2)
	v_cvt_f32_f16_e32 v56, v60
	s_waitcnt lgkmcnt(1)
	v_cvt_f32_f16_e32 v57, v61
	s_waitcnt lgkmcnt(0)
	v_cvt_f32_f16_e32 v58, v62
	v_lshlrev_b32_e32 v17, 16, v12
	v_and_b32_e32 v12, 0xffff0000, v12
	v_lshlrev_b32_e32 v54, 16, v13
	v_and_b32_e32 v13, 0xffff0000, v13
	v_add_u32_e32 v14, s14, v44
	v_mul_f32_e32 v17, v17, v15
	v_mul_f32_e32 v12, v12, v56
	v_mul_f32_e32 v54, v54, v57
	v_mul_f32_e32 v13, v13, v58
	v_mad_i64_i32 v[14:15], s[16:17], v14, s9, v[36:37]
	v_cvt_pk_bf16_f32 v10, v55, v10
	v_cvt_pk_bf16_f32 v11, v16, v11
	v_cvt_pk_bf16_f32 v12, v17, v12
	v_cvt_pk_bf16_f32 v13, v54, v13
	global_store_dwordx4 v[14:15], v[10:13], off offset:1024
	ds_read_u16 v15, v52
	ds_read_u16 v16, v52 offset:132
	ds_read_u16 v17, v52 offset:264
	ds_read_u16 v54, v52 offset:396
	ds_read_u16 v55, v52 offset:528
	ds_read_u16 v56, v52 offset:660
	ds_read_u16 v57, v52 offset:792
	ds_read_u16 v58, v52 offset:924
	s_waitcnt lgkmcnt(7)
	v_cvt_f32_f16_e32 v15, v15
	s_waitcnt lgkmcnt(6)
	v_cvt_f32_f16_e32 v16, v16
	s_waitcnt lgkmcnt(5)
	v_cvt_f32_f16_e32 v17, v17
	s_waitcnt lgkmcnt(4)
	v_cvt_f32_f16_e32 v54, v54
	s_waitcnt vmcnt(7)
	v_lshlrev_b32_e32 v11, 16, v6
	v_and_b32_e32 v6, 0xffff0000, v6
	v_lshlrev_b32_e32 v12, 16, v7
	v_and_b32_e32 v7, 0xffff0000, v7
	v_mul_f32_e32 v15, v11, v15
	v_mul_f32_e32 v6, v6, v16
	v_mul_f32_e32 v12, v12, v17
	v_mul_f32_e32 v7, v7, v54
	s_waitcnt lgkmcnt(3)
	v_cvt_f32_f16_e32 v11, v55
	s_waitcnt lgkmcnt(2)
	v_cvt_f32_f16_e32 v16, v56
	s_waitcnt lgkmcnt(1)
	v_cvt_f32_f16_e32 v17, v57
	s_waitcnt lgkmcnt(0)
	v_cvt_f32_f16_e32 v54, v58
	v_lshlrev_b32_e32 v13, 16, v8
	v_and_b32_e32 v8, 0xffff0000, v8
	v_lshlrev_b32_e32 v14, 16, v9
	v_and_b32_e32 v9, 0xffff0000, v9
	v_add_u32_e32 v10, s14, v45
	v_mul_f32_e32 v13, v13, v11
	v_mul_f32_e32 v8, v8, v16
	v_mul_f32_e32 v14, v14, v17
	v_mul_f32_e32 v9, v9, v54
	v_mad_i64_i32 v[10:11], s[16:17], v10, s9, v[36:37]
	v_cvt_pk_bf16_f32 v6, v15, v6
	v_cvt_pk_bf16_f32 v7, v12, v7
	v_cvt_pk_bf16_f32 v8, v13, v8
	v_cvt_pk_bf16_f32 v9, v14, v9
	global_store_dwordx4 v[10:11], v[6:9], off offset:1024
	ds_read_u16 v11, v53
	ds_read_u16 v12, v53 offset:132
	ds_read_u16 v13, v53 offset:264
	ds_read_u16 v14, v53 offset:396
	ds_read_u16 v15, v53 offset:528
	ds_read_u16 v16, v53 offset:660
	ds_read_u16 v17, v53 offset:792
	ds_read_u16 v54, v53 offset:924
	s_waitcnt lgkmcnt(7)
	v_cvt_f32_f16_e32 v11, v11
	s_waitcnt lgkmcnt(6)
	v_cvt_f32_f16_e32 v12, v12
	s_waitcnt lgkmcnt(5)
	v_cvt_f32_f16_e32 v13, v13
	s_waitcnt lgkmcnt(4)
	v_cvt_f32_f16_e32 v14, v14
	s_waitcnt vmcnt(7)
	v_lshlrev_b32_e32 v7, 16, v2
	v_and_b32_e32 v2, 0xffff0000, v2
	v_lshlrev_b32_e32 v8, 16, v3
	v_and_b32_e32 v3, 0xffff0000, v3
	v_mul_f32_e32 v11, v7, v11
	v_mul_f32_e32 v2, v2, v12
	v_mul_f32_e32 v8, v8, v13
	v_mul_f32_e32 v3, v3, v14
	s_waitcnt lgkmcnt(3)
	v_cvt_f32_f16_e32 v7, v15
	s_waitcnt lgkmcnt(2)
	v_cvt_f32_f16_e32 v12, v16
	s_waitcnt lgkmcnt(1)
	v_cvt_f32_f16_e32 v13, v17
	s_waitcnt lgkmcnt(0)
	v_cvt_f32_f16_e32 v14, v54
	v_lshlrev_b32_e32 v9, 16, v4
	v_and_b32_e32 v4, 0xffff0000, v4
	v_lshlrev_b32_e32 v10, 16, v5
	v_and_b32_e32 v5, 0xffff0000, v5
	v_add_u32_e32 v6, s14, v39
	v_mul_f32_e32 v9, v9, v7
	v_mul_f32_e32 v4, v4, v12
	v_mul_f32_e32 v10, v10, v13
	v_mul_f32_e32 v5, v5, v14
	v_mad_i64_i32 v[6:7], s[14:15], v6, s9, v[36:37]
	v_cvt_pk_bf16_f32 v2, v11, v2
	v_cvt_pk_bf16_f32 v3, v8, v3
	v_cvt_pk_bf16_f32 v4, v9, v4
	v_cvt_pk_bf16_f32 v5, v10, v5
	global_store_dwordx4 v[6:7], v[2:5], off offset:1024
	s_waitcnt lgkmcnt(0)
	s_addk_i32 s0, 0x80
	s_add_i32 s10, s10, s1
	s_cmpk_lt_i32 s0, 0x180
	s_cbranch_scc1 .LBB0_727
